# attention epilogue: lane-pair exchange through DPP instead of LDS permutes; row quantisation loops wait only for the staged loads
# baseline (speedup 1.0000x reference)
.LBB0_574:
	s_waitcnt vmcnt(5)
	v_mov_b32_e32 v14, v80
	v_mov_b32_e32 v15, v81
	v_mov_b32_e32 v16, v82
	v_mov_b32_e32 v17, v83
	v_mov_b32_e32 v18, v84
	v_mov_b32_e32 v19, v85
	v_mov_b32_e32 v20, v86
	v_mov_b32_e32 v21, v87
	v_mov_b32_e32 v22, v88
	v_mov_b32_e32 v23, v89
	v_mov_b32_e32 v24, v90
	v_mov_b32_e32 v25, v91
	v_mov_b32_e32 v26, v92
	v_mov_b32_e32 v27, v93
	v_mov_b32_e32 v28, v94
	v_mov_b32_e32 v29, v95
	v_mov_b32_e32 v97, v96
	v_readlane_b32 vcc_lo, v252, 5
	s_add_i32 vcc_lo, s6, vcc_lo
	s_cmpk_gt_i32 vcc_lo, 0x3fff
	s_cbranch_scc1 .Lrq_nopf
	v_lshl_add_u64 v[98:99], v[2:3], 0, s[10:11]
	global_load_dwordx4 v[80:83], v[98:99], off offset:-2048
	global_load_dwordx4 v[84:87], v[98:99], off offset:-1024
	global_load_dwordx4 v[88:91], v[98:99], off
	global_load_dwordx4 v[92:95], v[98:99], off offset:1024
	v_add_u32_e32 v100, s8, v12
	global_load_dword v96, v100, s[4:5]

.LBB0_1120:
	s_and_saveexec_b64 s[4:5], s[0:1]
	ds_write_b32 v183, v185
	s_or_b64 exec, exec, s[4:5]
	s_waitcnt lgkmcnt(0)
	ds_read_b128 v[76:79], v177
	ds_read_b128 v[72:75], v177 offset:32
	v_and_b32_e32 v80, 64, v191
	v_add_u32_e32 v80, 64, v80
	s_lshl_b32 s0, s14, 1
	s_waitcnt lgkmcnt(1)
	v_rcp_f32_e32 v82, v76
	v_lshlrev_b32_e32 v76, 1, v175
	v_lshl_or_b32 v148, v176, 10, v76
	v_xor_b32_e32 v76, 1, v191
	v_cmp_lt_i32_e32 vcc, v76, v80
	v_mul_f32_e32 v32, v32, v82
	s_add_u32 s0, s15, s0
	v_cndmask_b32_e32 v76, v191, v76, vcc
	v_lshlrev_b32_e32 v76, 2, v76
	ds_read_b128 v[68:71], v177 offset:64
	ds_read_b128 v[64:67], v177 offset:96
	s_nop 1
	v_mov_b32_dpp v83, v32 quad_perm:[1,0,3,2] row_mask:0xf bank_mask:0xf
	s_addc_u32 s1, s36, 0
	s_add_u32 s4, s0, s28
	s_addc_u32 s5, s1, s29
	v_and_b32_e32 v80, 1, v174
	v_cmp_eq_u32_e64 s[0:1], 0, v80
	v_lshl_add_u64 v[80:81], s[4:5], 0, v[148:149]
	s_and_saveexec_b64 s[4:5], s[0:1]
	s_cbranch_execz .LBB0_1124
	s_waitcnt lgkmcnt(0)
	v_cvt_pk_bf16_f32 v32, v32, v83
	global_store_dword v[80:81], v32, off
.LBB0_1124:
	s_or_b64 exec, exec, s[4:5]
	v_mul_f32_e32 v32, v48, v82
	s_nop 1
	v_mov_b32_dpp v48, v32 quad_perm:[1,0,3,2] row_mask:0xf bank_mask:0xf
	s_and_saveexec_b64 s[4:5], s[0:1]
	s_cbranch_execz .LBB0_1126
	s_waitcnt lgkmcnt(0)
	v_cvt_pk_bf16_f32 v32, v32, v48
	global_store_dword v[80:81], v32, off offset:64
.LBB0_1126:
	s_or_b64 exec, exec, s[4:5]
	v_mul_f32_e32 v16, v16, v82
	s_nop 1
	v_mov_b32_dpp v32, v16 quad_perm:[1,0,3,2] row_mask:0xf bank_mask:0xf
	s_and_saveexec_b64 s[4:5], s[0:1]
	s_cbranch_execz .LBB0_1128
	s_waitcnt lgkmcnt(0)
	v_cvt_pk_bf16_f32 v16, v16, v32
	global_store_dword v[80:81], v16, off offset:128
.LBB0_1128:
	s_or_b64 exec, exec, s[4:5]
	v_mul_f32_e32 v0, v0, v82
	s_nop 1
	v_mov_b32_dpp v16, v0 quad_perm:[1,0,3,2] row_mask:0xf bank_mask:0xf
	s_and_saveexec_b64 s[4:5], s[0:1]
	s_cbranch_execz .LBB0_1130
	s_waitcnt lgkmcnt(0)
	v_cvt_pk_bf16_f32 v0, v0, v16
	global_store_dword v[80:81], v0, off offset:192
.LBB0_1130:
	s_or_b64 exec, exec, s[4:5]
	v_rcp_f32_e32 v0, v77
	s_waitcnt lgkmcnt(0)
	v_mul_f32_e32 v16, v33, v0
	s_nop 1
	v_mov_b32_dpp v32, v16 quad_perm:[1,0,3,2] row_mask:0xf bank_mask:0xf
	s_and_saveexec_b64 s[4:5], s[0:1]
	s_cbranch_execz .LBB0_1132
	s_waitcnt lgkmcnt(0)
	v_cvt_pk_bf16_f32 v16, v16, v32
	global_store_dword v[80:81], v16, off offset:256
.LBB0_1132:
	s_or_b64 exec, exec, s[4:5]
	v_mul_f32_e32 v16, v49, v0
	s_waitcnt lgkmcnt(0)
	s_nop 1
	v_mov_b32_dpp v32, v16 quad_perm:[1,0,3,2] row_mask:0xf bank_mask:0xf
	s_and_saveexec_b64 s[4:5], s[0:1]
	s_cbranch_execz .LBB0_1134
	s_waitcnt lgkmcnt(0)
	v_cvt_pk_bf16_f32 v16, v16, v32
	global_store_dword v[80:81], v16, off offset:320
.LBB0_1134:
	s_or_b64 exec, exec, s[4:5]
	v_mul_f32_e32 v16, v17, v0
	s_nop 1
	v_mov_b32_dpp v17, v16 quad_perm:[1,0,3,2] row_mask:0xf bank_mask:0xf
	s_and_saveexec_b64 s[4:5], s[0:1]
	s_cbranch_execz .LBB0_1136
	s_waitcnt lgkmcnt(0)
	v_cvt_pk_bf16_f32 v16, v16, v17
	global_store_dword v[80:81], v16, off offset:384
.LBB0_1136:
	s_or_b64 exec, exec, s[4:5]
	v_mul_f32_e32 v0, v1, v0
	s_nop 1
	v_mov_b32_dpp v1, v0 quad_perm:[1,0,3,2] row_mask:0xf bank_mask:0xf
	s_and_saveexec_b64 s[4:5], s[0:1]
	s_cbranch_execz .LBB0_1138
	s_waitcnt lgkmcnt(0)
	v_cvt_pk_bf16_f32 v0, v0, v1
	global_store_dword v[80:81], v0, off offset:448
.LBB0_1138:
	s_or_b64 exec, exec, s[4:5]
	v_rcp_f32_e32 v0, v78
	s_waitcnt lgkmcnt(0)
	v_mul_f32_e32 v1, v34, v0
	s_nop 1
	v_mov_b32_dpp v16, v1 quad_perm:[1,0,3,2] row_mask:0xf bank_mask:0xf
	s_and_saveexec_b64 s[4:5], s[0:1]
	s_cbranch_execz .LBB0_1140
	s_waitcnt lgkmcnt(0)
	v_cvt_pk_bf16_f32 v1, v1, v16
	global_store_dword v[80:81], v1, off offset:512
.LBB0_1140:
	s_or_b64 exec, exec, s[4:5]
	v_mul_f32_e32 v1, v50, v0
	s_waitcnt lgkmcnt(0)
	s_nop 1
	v_mov_b32_dpp v16, v1 quad_perm:[1,0,3,2] row_mask:0xf bank_mask:0xf
	s_and_saveexec_b64 s[4:5], s[0:1]
	s_cbranch_execz .LBB0_1142
	s_waitcnt lgkmcnt(0)
	v_cvt_pk_bf16_f32 v1, v1, v16
	global_store_dword v[80:81], v1, off offset:576
.LBB0_1142:
	s_or_b64 exec, exec, s[4:5]
	v_mul_f32_e32 v1, v18, v0
	s_waitcnt lgkmcnt(0)
	s_nop 1
	v_mov_b32_dpp v16, v1 quad_perm:[1,0,3,2] row_mask:0xf bank_mask:0xf
	s_and_saveexec_b64 s[4:5], s[0:1]
	s_cbranch_execz .LBB0_1144
	s_waitcnt lgkmcnt(0)
	v_cvt_pk_bf16_f32 v1, v1, v16
	global_store_dword v[80:81], v1, off offset:640
.LBB0_1144:
	s_or_b64 exec, exec, s[4:5]
	v_mul_f32_e32 v0, v2, v0
	s_nop 1
	v_mov_b32_dpp v1, v0 quad_perm:[1,0,3,2] row_mask:0xf bank_mask:0xf
	s_and_saveexec_b64 s[4:5], s[0:1]
	s_cbranch_execz .LBB0_1146
	s_waitcnt lgkmcnt(0)
	v_cvt_pk_bf16_f32 v0, v0, v1
	global_store_dword v[80:81], v0, off offset:704
.LBB0_1146:
	s_or_b64 exec, exec, s[4:5]
	v_rcp_f32_e32 v0, v79
	s_waitcnt lgkmcnt(0)
	v_mul_f32_e32 v1, v35, v0
	s_nop 1
	v_mov_b32_dpp v2, v1 quad_perm:[1,0,3,2] row_mask:0xf bank_mask:0xf
	s_and_saveexec_b64 s[4:5], s[0:1]
	s_cbranch_execz .LBB0_1148
	s_waitcnt lgkmcnt(0)
	v_cvt_pk_bf16_f32 v1, v1, v2
	global_store_dword v[80:81], v1, off offset:768
.LBB0_1148:
	s_or_b64 exec, exec, s[4:5]
	v_mul_f32_e32 v1, v51, v0
	s_waitcnt lgkmcnt(0)
	s_nop 1
	v_mov_b32_dpp v2, v1 quad_perm:[1,0,3,2] row_mask:0xf bank_mask:0xf
	s_and_saveexec_b64 s[4:5], s[0:1]
	s_cbranch_execz .LBB0_1150
	s_waitcnt lgkmcnt(0)
	v_cvt_pk_bf16_f32 v1, v1, v2
	global_store_dword v[80:81], v1, off offset:832
.LBB0_1150:
	s_or_b64 exec, exec, s[4:5]
	v_mul_f32_e32 v1, v19, v0
	s_waitcnt lgkmcnt(0)
	s_nop 1
	v_mov_b32_dpp v2, v1 quad_perm:[1,0,3,2] row_mask:0xf bank_mask:0xf
	s_and_saveexec_b64 s[4:5], s[0:1]
	s_cbranch_execz .LBB0_1152
	s_waitcnt lgkmcnt(0)
	v_cvt_pk_bf16_f32 v1, v1, v2
	global_store_dword v[80:81], v1, off offset:896
.LBB0_1152:
	s_or_b64 exec, exec, s[4:5]
	v_mul_f32_e32 v0, v3, v0
	s_nop 1
	v_mov_b32_dpp v1, v0 quad_perm:[1,0,3,2] row_mask:0xf bank_mask:0xf
	s_and_saveexec_b64 s[4:5], s[0:1]
	s_cbranch_execz .LBB0_1154
	s_waitcnt lgkmcnt(0)
	v_cvt_pk_bf16_f32 v0, v0, v1
	global_store_dword v[80:81], v0, off offset:960
.LBB0_1154:
	s_or_b64 exec, exec, s[4:5]
	v_rcp_f32_e32 v0, v72
	s_waitcnt lgkmcnt(0)
	v_mul_f32_e32 v1, v36, v0
	s_nop 1
	v_mov_b32_dpp v2, v1 quad_perm:[1,0,3,2] row_mask:0xf bank_mask:0xf
	s_and_saveexec_b64 s[4:5], s[0:1]
	s_cbranch_execz .LBB0_1156
	s_waitcnt lgkmcnt(0)
	v_cvt_pk_bf16_f32 v1, v1, v2
	global_store_dword v[80:81], v1, off offset:2048
.LBB0_1156:
	s_or_b64 exec, exec, s[4:5]
	v_mul_f32_e32 v1, v52, v0
	s_waitcnt lgkmcnt(0)
	s_nop 1
	v_mov_b32_dpp v2, v1 quad_perm:[1,0,3,2] row_mask:0xf bank_mask:0xf
	s_and_saveexec_b64 s[4:5], s[0:1]
	s_cbranch_execz .LBB0_1158
	s_waitcnt lgkmcnt(0)
	v_cvt_pk_bf16_f32 v1, v1, v2
	global_store_dword v[80:81], v1, off offset:2112
.LBB0_1158:
	s_or_b64 exec, exec, s[4:5]
	v_mul_f32_e32 v1, v20, v0
	s_waitcnt lgkmcnt(0)
	s_nop 1
	v_mov_b32_dpp v2, v1 quad_perm:[1,0,3,2] row_mask:0xf bank_mask:0xf
	s_and_saveexec_b64 s[4:5], s[0:1]
	s_cbranch_execz .LBB0_1160
	s_waitcnt lgkmcnt(0)
	v_cvt_pk_bf16_f32 v1, v1, v2
	global_store_dword v[80:81], v1, off offset:2176
.LBB0_1160:
	s_or_b64 exec, exec, s[4:5]
	v_mul_f32_e32 v0, v4, v0
	s_nop 1
	v_mov_b32_dpp v1, v0 quad_perm:[1,0,3,2] row_mask:0xf bank_mask:0xf
	s_and_saveexec_b64 s[4:5], s[0:1]
	s_cbranch_execz .LBB0_1162
	s_waitcnt lgkmcnt(0)
	v_cvt_pk_bf16_f32 v0, v0, v1
	global_store_dword v[80:81], v0, off offset:2240
.LBB0_1162:
	s_or_b64 exec, exec, s[4:5]
	v_rcp_f32_e32 v0, v73
	s_waitcnt lgkmcnt(0)
	v_mul_f32_e32 v1, v37, v0
	s_nop 1
	v_mov_b32_dpp v2, v1 quad_perm:[1,0,3,2] row_mask:0xf bank_mask:0xf
	s_and_saveexec_b64 s[4:5], s[0:1]
	s_cbranch_execz .LBB0_1164
	s_waitcnt lgkmcnt(0)
	v_cvt_pk_bf16_f32 v1, v1, v2
	global_store_dword v[80:81], v1, off offset:2304
.LBB0_1164:
	s_or_b64 exec, exec, s[4:5]
	v_mul_f32_e32 v1, v53, v0
	s_waitcnt lgkmcnt(0)
	s_nop 1
	v_mov_b32_dpp v2, v1 quad_perm:[1,0,3,2] row_mask:0xf bank_mask:0xf
	s_and_saveexec_b64 s[4:5], s[0:1]
	s_cbranch_execz .LBB0_1166
	s_waitcnt lgkmcnt(0)
	v_cvt_pk_bf16_f32 v1, v1, v2
	global_store_dword v[80:81], v1, off offset:2368
.LBB0_1166:
	s_or_b64 exec, exec, s[4:5]
	v_mul_f32_e32 v1, v21, v0
	s_waitcnt lgkmcnt(0)
	s_nop 1
	v_mov_b32_dpp v2, v1 quad_perm:[1,0,3,2] row_mask:0xf bank_mask:0xf
	s_and_saveexec_b64 s[4:5], s[0:1]
	s_cbranch_execz .LBB0_1168
	s_waitcnt lgkmcnt(0)
	v_cvt_pk_bf16_f32 v1, v1, v2
	global_store_dword v[80:81], v1, off offset:2432
.LBB0_1168:
	s_or_b64 exec, exec, s[4:5]
	v_mul_f32_e32 v0, v5, v0
	s_nop 1
	v_mov_b32_dpp v1, v0 quad_perm:[1,0,3,2] row_mask:0xf bank_mask:0xf
	s_and_saveexec_b64 s[4:5], s[0:1]
	s_cbranch_execz .LBB0_1170
	s_waitcnt lgkmcnt(0)
	v_cvt_pk_bf16_f32 v0, v0, v1
	global_store_dword v[80:81], v0, off offset:2496
.LBB0_1170:
	s_or_b64 exec, exec, s[4:5]
	v_rcp_f32_e32 v0, v74
	s_waitcnt lgkmcnt(0)
	v_mul_f32_e32 v1, v38, v0
	s_nop 1
	v_mov_b32_dpp v2, v1 quad_perm:[1,0,3,2] row_mask:0xf bank_mask:0xf
	s_and_saveexec_b64 s[4:5], s[0:1]
	s_cbranch_execz .LBB0_1172
	s_waitcnt lgkmcnt(0)
	v_cvt_pk_bf16_f32 v1, v1, v2
	global_store_dword v[80:81], v1, off offset:2560
.LBB0_1172:
	s_or_b64 exec, exec, s[4:5]
	v_mul_f32_e32 v1, v54, v0
	s_waitcnt lgkmcnt(0)
	s_nop 1
	v_mov_b32_dpp v2, v1 quad_perm:[1,0,3,2] row_mask:0xf bank_mask:0xf
	s_and_saveexec_b64 s[4:5], s[0:1]
	s_cbranch_execz .LBB0_1174
	s_waitcnt lgkmcnt(0)
	v_cvt_pk_bf16_f32 v1, v1, v2
	global_store_dword v[80:81], v1, off offset:2624
.LBB0_1174:
	s_or_b64 exec, exec, s[4:5]
	v_mul_f32_e32 v1, v22, v0
	s_waitcnt lgkmcnt(0)
	s_nop 1
	v_mov_b32_dpp v2, v1 quad_perm:[1,0,3,2] row_mask:0xf bank_mask:0xf
	s_and_saveexec_b64 s[4:5], s[0:1]
	s_cbranch_execz .LBB0_1176
	s_waitcnt lgkmcnt(0)
	v_cvt_pk_bf16_f32 v1, v1, v2
	global_store_dword v[80:81], v1, off offset:2688
.LBB0_1176:
	s_or_b64 exec, exec, s[4:5]
	v_mul_f32_e32 v0, v6, v0
	s_nop 1
	v_mov_b32_dpp v1, v0 quad_perm:[1,0,3,2] row_mask:0xf bank_mask:0xf
	s_and_saveexec_b64 s[4:5], s[0:1]
	s_cbranch_execz .LBB0_1178
	s_waitcnt lgkmcnt(0)
	v_cvt_pk_bf16_f32 v0, v0, v1
	global_store_dword v[80:81], v0, off offset:2752
.LBB0_1178:
	s_or_b64 exec, exec, s[4:5]
	v_rcp_f32_e32 v0, v75
	s_waitcnt lgkmcnt(0)
	v_mul_f32_e32 v1, v39, v0
	s_nop 1
	v_mov_b32_dpp v2, v1 quad_perm:[1,0,3,2] row_mask:0xf bank_mask:0xf
	s_and_saveexec_b64 s[4:5], s[0:1]
	s_cbranch_execz .LBB0_1180
	s_waitcnt lgkmcnt(0)
	v_cvt_pk_bf16_f32 v1, v1, v2
	global_store_dword v[80:81], v1, off offset:2816
.LBB0_1180:
	s_or_b64 exec, exec, s[4:5]
	v_mul_f32_e32 v1, v55, v0
	s_waitcnt lgkmcnt(0)
	s_nop 1
	v_mov_b32_dpp v2, v1 quad_perm:[1,0,3,2] row_mask:0xf bank_mask:0xf
	s_and_saveexec_b64 s[4:5], s[0:1]
	s_cbranch_execz .LBB0_1182
	s_waitcnt lgkmcnt(0)
	v_cvt_pk_bf16_f32 v1, v1, v2
	global_store_dword v[80:81], v1, off offset:2880
.LBB0_1182:
	s_or_b64 exec, exec, s[4:5]
	v_mul_f32_e32 v1, v23, v0
	s_waitcnt lgkmcnt(0)
	s_nop 1
	v_mov_b32_dpp v2, v1 quad_perm:[1,0,3,2] row_mask:0xf bank_mask:0xf
	s_and_saveexec_b64 s[4:5], s[0:1]
	s_cbranch_execz .LBB0_1184
	s_waitcnt lgkmcnt(0)
	v_cvt_pk_bf16_f32 v1, v1, v2
	global_store_dword v[80:81], v1, off offset:2944
.LBB0_1184:
	s_or_b64 exec, exec, s[4:5]
	v_mul_f32_e32 v0, v7, v0
	s_nop 1
	v_mov_b32_dpp v1, v0 quad_perm:[1,0,3,2] row_mask:0xf bank_mask:0xf
	s_and_saveexec_b64 s[4:5], s[0:1]
	s_cbranch_execz .LBB0_1186
	s_waitcnt lgkmcnt(0)
	v_cvt_pk_bf16_f32 v0, v0, v1
	global_store_dword v[80:81], v0, off offset:3008
.LBB0_1186:
	s_or_b64 exec, exec, s[4:5]
	v_rcp_f32_e32 v0, v68
	s_waitcnt lgkmcnt(0)
	v_mul_f32_e32 v1, v40, v0
	s_nop 1
	v_mov_b32_dpp v2, v1 quad_perm:[1,0,3,2] row_mask:0xf bank_mask:0xf
	s_and_saveexec_b64 s[4:5], s[0:1]
	s_cbranch_execz .LBB0_1188
	s_waitcnt lgkmcnt(0)
	v_cvt_pk_bf16_f32 v1, v1, v2
	v_add_co_u32_e32 v2, vcc, 0x1000, v80
	s_nop 1
	v_addc_co_u32_e32 v3, vcc, 0, v81, vcc
	global_store_dword v[2:3], v1, off
.LBB0_1188:
	s_or_b64 exec, exec, s[4:5]
	v_mul_f32_e32 v1, v56, v0
	s_waitcnt lgkmcnt(0)
	s_nop 1
	v_mov_b32_dpp v2, v1 quad_perm:[1,0,3,2] row_mask:0xf bank_mask:0xf
	s_and_saveexec_b64 s[4:5], s[0:1]
	s_cbranch_execz .LBB0_1190
	s_waitcnt lgkmcnt(0)
	v_cvt_pk_bf16_f32 v1, v1, v2
	v_add_co_u32_e32 v2, vcc, 0x1000, v80
	s_nop 1
	v_addc_co_u32_e32 v3, vcc, 0, v81, vcc
	global_store_dword v[2:3], v1, off offset:64
.LBB0_1190:
	s_or_b64 exec, exec, s[4:5]
	v_mul_f32_e32 v1, v24, v0
	s_waitcnt lgkmcnt(0)
	s_nop 1
	v_mov_b32_dpp v2, v1 quad_perm:[1,0,3,2] row_mask:0xf bank_mask:0xf
	s_and_saveexec_b64 s[4:5], s[0:1]
	s_cbranch_execz .LBB0_1192
	s_waitcnt lgkmcnt(0)
	v_cvt_pk_bf16_f32 v1, v1, v2
	v_add_co_u32_e32 v2, vcc, 0x1000, v80
	s_nop 1
	v_addc_co_u32_e32 v3, vcc, 0, v81, vcc
	global_store_dword v[2:3], v1, off offset:128
.LBB0_1192:
	s_or_b64 exec, exec, s[4:5]
	v_mul_f32_e32 v0, v8, v0
	s_nop 1
	v_mov_b32_dpp v1, v0 quad_perm:[1,0,3,2] row_mask:0xf bank_mask:0xf
	s_and_saveexec_b64 s[4:5], s[0:1]
	s_cbranch_execz .LBB0_1194
	s_waitcnt lgkmcnt(0)
	v_cvt_pk_bf16_f32 v2, v0, v1
	v_add_co_u32_e32 v0, vcc, 0x1000, v80
	s_nop 1
	v_addc_co_u32_e32 v1, vcc, 0, v81, vcc
	global_store_dword v[0:1], v2, off offset:192
.LBB0_1194:
	s_or_b64 exec, exec, s[4:5]
	v_rcp_f32_e32 v0, v69
	s_waitcnt lgkmcnt(0)
	v_mul_f32_e32 v1, v41, v0
	s_nop 1
	v_mov_b32_dpp v2, v1 quad_perm:[1,0,3,2] row_mask:0xf bank_mask:0xf
	s_and_saveexec_b64 s[4:5], s[0:1]
	s_cbranch_execz .LBB0_1196
	s_waitcnt lgkmcnt(0)
	v_cvt_pk_bf16_f32 v1, v1, v2
	v_add_co_u32_e32 v2, vcc, 0x1000, v80
	s_nop 1
	v_addc_co_u32_e32 v3, vcc, 0, v81, vcc
	global_store_dword v[2:3], v1, off offset:256
.LBB0_1196:
	s_or_b64 exec, exec, s[4:5]
	v_mul_f32_e32 v1, v57, v0
	s_waitcnt lgkmcnt(0)
	s_nop 1
	v_mov_b32_dpp v2, v1 quad_perm:[1,0,3,2] row_mask:0xf bank_mask:0xf
	s_and_saveexec_b64 s[4:5], s[0:1]
	s_cbranch_execz .LBB0_1198
	s_waitcnt lgkmcnt(0)
	v_cvt_pk_bf16_f32 v1, v1, v2
	v_add_co_u32_e32 v2, vcc, 0x1000, v80
	s_nop 1
	v_addc_co_u32_e32 v3, vcc, 0, v81, vcc
	global_store_dword v[2:3], v1, off offset:320
.LBB0_1198:
	s_or_b64 exec, exec, s[4:5]
	v_mul_f32_e32 v1, v25, v0
	s_waitcnt lgkmcnt(0)
	s_nop 1
	v_mov_b32_dpp v2, v1 quad_perm:[1,0,3,2] row_mask:0xf bank_mask:0xf
	s_and_saveexec_b64 s[4:5], s[0:1]
	s_cbranch_execz .LBB0_1200
	s_waitcnt lgkmcnt(0)
	v_cvt_pk_bf16_f32 v1, v1, v2
	v_add_co_u32_e32 v2, vcc, 0x1000, v80
	s_nop 1
	v_addc_co_u32_e32 v3, vcc, 0, v81, vcc
	global_store_dword v[2:3], v1, off offset:384
.LBB0_1200:
	s_or_b64 exec, exec, s[4:5]
	v_mul_f32_e32 v0, v9, v0
	s_nop 1
	v_mov_b32_dpp v1, v0 quad_perm:[1,0,3,2] row_mask:0xf bank_mask:0xf
	s_and_saveexec_b64 s[4:5], s[0:1]
	s_cbranch_execz .LBB0_1202
	s_waitcnt lgkmcnt(0)
	v_cvt_pk_bf16_f32 v2, v0, v1
	v_add_co_u32_e32 v0, vcc, 0x1000, v80
	s_nop 1
	v_addc_co_u32_e32 v1, vcc, 0, v81, vcc
	global_store_dword v[0:1], v2, off offset:448
.LBB0_1202:
	s_or_b64 exec, exec, s[4:5]
	v_rcp_f32_e32 v0, v70
	s_waitcnt lgkmcnt(0)
	v_mul_f32_e32 v1, v42, v0
	s_nop 1
	v_mov_b32_dpp v2, v1 quad_perm:[1,0,3,2] row_mask:0xf bank_mask:0xf
	s_and_saveexec_b64 s[4:5], s[0:1]
	s_cbranch_execz .LBB0_1204
	s_waitcnt lgkmcnt(0)
	v_cvt_pk_bf16_f32 v1, v1, v2
	v_add_co_u32_e32 v2, vcc, 0x1000, v80
	s_nop 1
	v_addc_co_u32_e32 v3, vcc, 0, v81, vcc
	global_store_dword v[2:3], v1, off offset:512
.LBB0_1204:
	s_or_b64 exec, exec, s[4:5]
	v_mul_f32_e32 v1, v58, v0
	s_waitcnt lgkmcnt(0)
	s_nop 1
	v_mov_b32_dpp v2, v1 quad_perm:[1,0,3,2] row_mask:0xf bank_mask:0xf
	s_and_saveexec_b64 s[4:5], s[0:1]
	s_cbranch_execz .LBB0_1206
	s_waitcnt lgkmcnt(0)
	v_cvt_pk_bf16_f32 v1, v1, v2
	v_add_co_u32_e32 v2, vcc, 0x1000, v80
	s_nop 1
	v_addc_co_u32_e32 v3, vcc, 0, v81, vcc
	global_store_dword v[2:3], v1, off offset:576
.LBB0_1206:
	s_or_b64 exec, exec, s[4:5]
	v_mul_f32_e32 v1, v26, v0
	s_waitcnt lgkmcnt(0)
	s_nop 1
	v_mov_b32_dpp v2, v1 quad_perm:[1,0,3,2] row_mask:0xf bank_mask:0xf
	s_and_saveexec_b64 s[4:5], s[0:1]
	s_cbranch_execz .LBB0_1208
	s_waitcnt lgkmcnt(0)
	v_cvt_pk_bf16_f32 v1, v1, v2
	v_add_co_u32_e32 v2, vcc, 0x1000, v80
	s_nop 1
	v_addc_co_u32_e32 v3, vcc, 0, v81, vcc
	global_store_dword v[2:3], v1, off offset:640
.LBB0_1208:
	s_or_b64 exec, exec, s[4:5]
	v_mul_f32_e32 v0, v10, v0
	s_nop 1
	v_mov_b32_dpp v1, v0 quad_perm:[1,0,3,2] row_mask:0xf bank_mask:0xf
	s_and_saveexec_b64 s[4:5], s[0:1]
	s_cbranch_execz .LBB0_1210
	s_waitcnt lgkmcnt(0)
	v_cvt_pk_bf16_f32 v2, v0, v1
	v_add_co_u32_e32 v0, vcc, 0x1000, v80
	s_nop 1
	v_addc_co_u32_e32 v1, vcc, 0, v81, vcc
	global_store_dword v[0:1], v2, off offset:704
.LBB0_1210:
	s_or_b64 exec, exec, s[4:5]
	v_rcp_f32_e32 v0, v71
	s_waitcnt lgkmcnt(0)
	v_mul_f32_e32 v1, v43, v0
	s_nop 1
	v_mov_b32_dpp v2, v1 quad_perm:[1,0,3,2] row_mask:0xf bank_mask:0xf
	s_and_saveexec_b64 s[4:5], s[0:1]
	s_cbranch_execz .LBB0_1212
	s_waitcnt lgkmcnt(0)
	v_cvt_pk_bf16_f32 v1, v1, v2
	v_add_co_u32_e32 v2, vcc, 0x1000, v80
	s_nop 1
	v_addc_co_u32_e32 v3, vcc, 0, v81, vcc
	global_store_dword v[2:3], v1, off offset:768
.LBB0_1212:
	s_or_b64 exec, exec, s[4:5]
	v_mul_f32_e32 v1, v59, v0
	s_waitcnt lgkmcnt(0)
	s_nop 1
	v_mov_b32_dpp v2, v1 quad_perm:[1,0,3,2] row_mask:0xf bank_mask:0xf
	s_and_saveexec_b64 s[4:5], s[0:1]
	s_cbranch_execz .LBB0_1214
	s_waitcnt lgkmcnt(0)
	v_cvt_pk_bf16_f32 v1, v1, v2
	v_add_co_u32_e32 v2, vcc, 0x1000, v80
	s_nop 1
	v_addc_co_u32_e32 v3, vcc, 0, v81, vcc
	global_store_dword v[2:3], v1, off offset:832
.LBB0_1214:
	s_or_b64 exec, exec, s[4:5]
	v_mul_f32_e32 v1, v27, v0
	s_waitcnt lgkmcnt(0)
	s_nop 1
	v_mov_b32_dpp v2, v1 quad_perm:[1,0,3,2] row_mask:0xf bank_mask:0xf
	s_and_saveexec_b64 s[4:5], s[0:1]
	s_cbranch_execz .LBB0_1216
	s_waitcnt lgkmcnt(0)
	v_cvt_pk_bf16_f32 v1, v1, v2
	v_add_co_u32_e32 v2, vcc, 0x1000, v80
	s_nop 1
	v_addc_co_u32_e32 v3, vcc, 0, v81, vcc
	global_store_dword v[2:3], v1, off offset:896
.LBB0_1216:
	s_or_b64 exec, exec, s[4:5]
	v_mul_f32_e32 v0, v11, v0
	s_nop 1
	v_mov_b32_dpp v1, v0 quad_perm:[1,0,3,2] row_mask:0xf bank_mask:0xf
	s_and_saveexec_b64 s[4:5], s[0:1]
	s_cbranch_execz .LBB0_1218
	s_waitcnt lgkmcnt(0)
	v_cvt_pk_bf16_f32 v2, v0, v1
	v_add_co_u32_e32 v0, vcc, 0x1000, v80
	s_nop 1
	v_addc_co_u32_e32 v1, vcc, 0, v81, vcc
	global_store_dword v[0:1], v2, off offset:960
.LBB0_1218:
	s_or_b64 exec, exec, s[4:5]
	v_rcp_f32_e32 v0, v64
	s_waitcnt lgkmcnt(0)
	v_mul_f32_e32 v1, v44, v0
	s_nop 1
	v_mov_b32_dpp v2, v1 quad_perm:[1,0,3,2] row_mask:0xf bank_mask:0xf
	s_and_saveexec_b64 s[4:5], s[0:1]
	s_cbranch_execz .LBB0_1220
	s_waitcnt lgkmcnt(0)
	v_cvt_pk_bf16_f32 v1, v1, v2
	v_add_co_u32_e32 v2, vcc, 0x1000, v80
	s_nop 1
	v_addc_co_u32_e32 v3, vcc, 0, v81, vcc
	global_store_dword v[2:3], v1, off offset:2048
.LBB0_1220:
	s_or_b64 exec, exec, s[4:5]
	v_mul_f32_e32 v1, v60, v0
	s_waitcnt lgkmcnt(0)
	s_nop 1
	v_mov_b32_dpp v2, v1 quad_perm:[1,0,3,2] row_mask:0xf bank_mask:0xf
	s_and_saveexec_b64 s[4:5], s[0:1]
	s_cbranch_execz .LBB0_1222
	s_waitcnt lgkmcnt(0)
	v_cvt_pk_bf16_f32 v1, v1, v2
	v_add_co_u32_e32 v2, vcc, 0x1000, v80
	s_nop 1
	v_addc_co_u32_e32 v3, vcc, 0, v81, vcc
	global_store_dword v[2:3], v1, off offset:2112
.LBB0_1222:
	s_or_b64 exec, exec, s[4:5]
	v_mul_f32_e32 v1, v28, v0
	s_waitcnt lgkmcnt(0)
	s_nop 1
	v_mov_b32_dpp v2, v1 quad_perm:[1,0,3,2] row_mask:0xf bank_mask:0xf
	s_and_saveexec_b64 s[4:5], s[0:1]
	s_cbranch_execz .LBB0_1224
	s_waitcnt lgkmcnt(0)
	v_cvt_pk_bf16_f32 v1, v1, v2
	v_add_co_u32_e32 v2, vcc, 0x1000, v80
	s_nop 1
	v_addc_co_u32_e32 v3, vcc, 0, v81, vcc
	global_store_dword v[2:3], v1, off offset:2176
.LBB0_1224:
	s_or_b64 exec, exec, s[4:5]
	v_mul_f32_e32 v0, v12, v0
	s_nop 1
	v_mov_b32_dpp v1, v0 quad_perm:[1,0,3,2] row_mask:0xf bank_mask:0xf
	s_and_saveexec_b64 s[4:5], s[0:1]
	s_cbranch_execz .LBB0_1226
	s_waitcnt lgkmcnt(0)
	v_cvt_pk_bf16_f32 v2, v0, v1
	v_add_co_u32_e32 v0, vcc, 0x1000, v80
	s_nop 1
	v_addc_co_u32_e32 v1, vcc, 0, v81, vcc
	global_store_dword v[0:1], v2, off offset:2240
.LBB0_1226:
	s_or_b64 exec, exec, s[4:5]
	v_rcp_f32_e32 v0, v65
	s_waitcnt lgkmcnt(0)
	v_mul_f32_e32 v1, v45, v0
	s_nop 1
	v_mov_b32_dpp v2, v1 quad_perm:[1,0,3,2] row_mask:0xf bank_mask:0xf
	s_and_saveexec_b64 s[4:5], s[0:1]
	s_cbranch_execz .LBB0_1228
	s_waitcnt lgkmcnt(0)
	v_cvt_pk_bf16_f32 v1, v1, v2
	v_add_co_u32_e32 v2, vcc, 0x1000, v80
	s_nop 1
	v_addc_co_u32_e32 v3, vcc, 0, v81, vcc
	global_store_dword v[2:3], v1, off offset:2304
.LBB0_1228:
	s_or_b64 exec, exec, s[4:5]
	v_mul_f32_e32 v1, v61, v0
	s_waitcnt lgkmcnt(0)
	s_nop 1
	v_mov_b32_dpp v2, v1 quad_perm:[1,0,3,2] row_mask:0xf bank_mask:0xf
	s_and_saveexec_b64 s[4:5], s[0:1]
	s_cbranch_execz .LBB0_1230
	s_waitcnt lgkmcnt(0)
	v_cvt_pk_bf16_f32 v1, v1, v2
	v_add_co_u32_e32 v2, vcc, 0x1000, v80
	s_nop 1
	v_addc_co_u32_e32 v3, vcc, 0, v81, vcc
	global_store_dword v[2:3], v1, off offset:2368
.LBB0_1230:
	s_or_b64 exec, exec, s[4:5]
	v_mul_f32_e32 v1, v29, v0
	s_waitcnt lgkmcnt(0)
	s_nop 1
	v_mov_b32_dpp v2, v1 quad_perm:[1,0,3,2] row_mask:0xf bank_mask:0xf
	s_and_saveexec_b64 s[4:5], s[0:1]
	s_cbranch_execz .LBB0_1232
	s_waitcnt lgkmcnt(0)
	v_cvt_pk_bf16_f32 v1, v1, v2
	v_add_co_u32_e32 v2, vcc, 0x1000, v80
	s_nop 1
	v_addc_co_u32_e32 v3, vcc, 0, v81, vcc
	global_store_dword v[2:3], v1, off offset:2432
.LBB0_1232:
	s_or_b64 exec, exec, s[4:5]
	v_mul_f32_e32 v0, v13, v0
	s_nop 1
	v_mov_b32_dpp v1, v0 quad_perm:[1,0,3,2] row_mask:0xf bank_mask:0xf
	s_and_saveexec_b64 s[4:5], s[0:1]
	s_cbranch_execz .LBB0_1234
	s_waitcnt lgkmcnt(0)
	v_cvt_pk_bf16_f32 v2, v0, v1
	v_add_co_u32_e32 v0, vcc, 0x1000, v80
	s_nop 1
	v_addc_co_u32_e32 v1, vcc, 0, v81, vcc
	global_store_dword v[0:1], v2, off offset:2496
.LBB0_1234:
	s_or_b64 exec, exec, s[4:5]
	v_rcp_f32_e32 v0, v66
	s_waitcnt lgkmcnt(0)
	v_mul_f32_e32 v1, v46, v0
	s_nop 1
	v_mov_b32_dpp v2, v1 quad_perm:[1,0,3,2] row_mask:0xf bank_mask:0xf
	s_and_saveexec_b64 s[4:5], s[0:1]
	s_cbranch_execz .LBB0_1236
	s_waitcnt lgkmcnt(0)
	v_cvt_pk_bf16_f32 v1, v1, v2
	v_add_co_u32_e32 v2, vcc, 0x1000, v80
	s_nop 1
	v_addc_co_u32_e32 v3, vcc, 0, v81, vcc
	global_store_dword v[2:3], v1, off offset:2560
.LBB0_1236:
	s_or_b64 exec, exec, s[4:5]
	v_mul_f32_e32 v1, v62, v0
	s_waitcnt lgkmcnt(0)
	s_nop 1
	v_mov_b32_dpp v2, v1 quad_perm:[1,0,3,2] row_mask:0xf bank_mask:0xf
	s_and_saveexec_b64 s[4:5], s[0:1]
	s_cbranch_execz .LBB0_1238
	s_waitcnt lgkmcnt(0)
	v_cvt_pk_bf16_f32 v1, v1, v2
	v_add_co_u32_e32 v2, vcc, 0x1000, v80
	s_nop 1
	v_addc_co_u32_e32 v3, vcc, 0, v81, vcc
	global_store_dword v[2:3], v1, off offset:2624
.LBB0_1238:
	s_or_b64 exec, exec, s[4:5]
	v_mul_f32_e32 v1, v30, v0
	s_waitcnt lgkmcnt(0)
	s_nop 1
	v_mov_b32_dpp v2, v1 quad_perm:[1,0,3,2] row_mask:0xf bank_mask:0xf
	s_and_saveexec_b64 s[4:5], s[0:1]
	s_cbranch_execz .LBB0_1240
	s_waitcnt lgkmcnt(0)
	v_cvt_pk_bf16_f32 v1, v1, v2
	v_add_co_u32_e32 v2, vcc, 0x1000, v80
	s_nop 1
	v_addc_co_u32_e32 v3, vcc, 0, v81, vcc
	global_store_dword v[2:3], v1, off offset:2688
.LBB0_1240:
	s_or_b64 exec, exec, s[4:5]
	v_mul_f32_e32 v0, v14, v0
	s_nop 1
	v_mov_b32_dpp v1, v0 quad_perm:[1,0,3,2] row_mask:0xf bank_mask:0xf
	s_and_saveexec_b64 s[4:5], s[0:1]
	s_cbranch_execz .LBB0_1242
	s_waitcnt lgkmcnt(0)
	v_cvt_pk_bf16_f32 v2, v0, v1
	v_add_co_u32_e32 v0, vcc, 0x1000, v80
	s_nop 1
	v_addc_co_u32_e32 v1, vcc, 0, v81, vcc
	global_store_dword v[0:1], v2, off offset:2752
.LBB0_1242:
	s_or_b64 exec, exec, s[4:5]
	v_rcp_f32_e32 v0, v67
	s_waitcnt lgkmcnt(0)
	v_mul_f32_e32 v1, v47, v0
	s_nop 1
	v_mov_b32_dpp v2, v1 quad_perm:[1,0,3,2] row_mask:0xf bank_mask:0xf
	s_and_saveexec_b64 s[4:5], s[0:1]
	s_cbranch_execz .LBB0_1244
	s_waitcnt lgkmcnt(0)
	v_cvt_pk_bf16_f32 v1, v1, v2
	v_add_co_u32_e32 v2, vcc, 0x1000, v80
	s_nop 1
	v_addc_co_u32_e32 v3, vcc, 0, v81, vcc
	global_store_dword v[2:3], v1, off offset:2816
.LBB0_1244:
	s_or_b64 exec, exec, s[4:5]
	v_mul_f32_e32 v1, v63, v0
	s_waitcnt lgkmcnt(0)
	s_nop 1
	v_mov_b32_dpp v2, v1 quad_perm:[1,0,3,2] row_mask:0xf bank_mask:0xf
	s_and_saveexec_b64 s[4:5], s[0:1]
	s_cbranch_execz .LBB0_1246
	s_waitcnt lgkmcnt(0)
	v_cvt_pk_bf16_f32 v1, v1, v2
	v_add_co_u32_e32 v2, vcc, 0x1000, v80
	s_nop 1
	v_addc_co_u32_e32 v3, vcc, 0, v81, vcc
	global_store_dword v[2:3], v1, off offset:2880
.LBB0_1246:
	s_or_b64 exec, exec, s[4:5]
	v_mul_f32_e32 v1, v31, v0
	s_waitcnt lgkmcnt(0)
	s_nop 1
	v_mov_b32_dpp v2, v1 quad_perm:[1,0,3,2] row_mask:0xf bank_mask:0xf
	s_and_saveexec_b64 s[4:5], s[0:1]
	s_cbranch_execz .LBB0_1248
	s_waitcnt lgkmcnt(0)
	v_cvt_pk_bf16_f32 v1, v1, v2
	v_add_co_u32_e32 v2, vcc, 0x1000, v80
	s_nop 1
	v_addc_co_u32_e32 v3, vcc, 0, v81, vcc
	global_store_dword v[2:3], v1, off offset:2944
.LBB0_1248:
	s_or_b64 exec, exec, s[4:5]
	v_mul_f32_e32 v0, v15, v0
	s_nop 1
	v_mov_b32_dpp v1, v0 quad_perm:[1,0,3,2] row_mask:0xf bank_mask:0xf
	s_and_saveexec_b64 s[4:5], s[0:1]
	s_cbranch_execz .LBB0_1097
	s_waitcnt lgkmcnt(0)
	v_cvt_pk_bf16_f32 v2, v0, v1
	v_add_co_u32_e32 v0, vcc, 0x1000, v80
	s_nop 1
	v_addc_co_u32_e32 v1, vcc, 0, v81, vcc
	global_store_dword v[0:1], v2, off offset:3008
	s_branch .LBB0_1097

.LBB0_1907:
	s_waitcnt vmcnt(5)
	v_mov_b32_e32 v80, v60
	v_mov_b32_e32 v81, v61
	v_mov_b32_e32 v82, v62
	v_mov_b32_e32 v83, v63
	v_mov_b32_e32 v84, v64
	v_mov_b32_e32 v85, v65
	v_mov_b32_e32 v86, v66
	v_mov_b32_e32 v87, v67
	v_mov_b32_e32 v88, v68
	v_mov_b32_e32 v89, v69
	v_mov_b32_e32 v90, v70
	v_mov_b32_e32 v91, v71
	v_mov_b32_e32 v92, v72
	v_mov_b32_e32 v93, v73
	v_mov_b32_e32 v94, v74
	v_mov_b32_e32 v95, v75
	v_mov_b32_e32 v96, v76
	v_readlane_b32 vcc_lo, v252, 5
	s_add_i32 vcc_lo, s12, vcc_lo
	s_cmpk_gt_i32 vcc_lo, 0x3fff
	s_cbranch_scc1 .Lrq6_nopf
	v_lshl_add_u64 v[98:99], v[2:3], 0, s[6:7]
	global_load_dwordx4 v[60:63], v[98:99], off offset:-2048
	global_load_dwordx4 v[64:67], v[98:99], off offset:-1024
	global_load_dwordx4 v[68:71], v[98:99], off
	global_load_dwordx4 v[72:75], v[98:99], off offset:1024
	v_add_u32_e32 v100, s4, v12
	global_load_dword v76, v100, s[2:3]
